# weight conversion: the 32 per-k norm-gain loads of each w_in / w_up item issued together instead of one-at-a-time with vmcnt(0)
# speedup vs baseline: 1.0395x; 1.0109x over previous
.LBB0_48:
	s_or_b64 exec, exec, s[4:5]
	s_lshl_b32 s14, s14, 6
	v_or_b32_e32 v27, s14, v3
	v_mov_b64_e32 v[12:13], s[0:1]
	s_mov_b32 s4, 0x8810
	v_mad_i64_i32 v[12:13], s[4:5], v27, s4, v[12:13]
	v_cmp_lt_i32_e64 s[4:5], -1, v0
	s_mov_b32 s6, 0x22000
	s_ashr_i32 s15, s14, 31
	v_cndmask_b32_e64 v0, 0, v0, s[4:5]
	v_lshl_add_u64 v[12:13], v[0:1], 2, v[12:13]
	v_add_co_u32_e32 v28, vcc, 0x11000, v12
	s_nop 1
	v_addc_co_u32_e32 v29, vcc, 0, v13, vcc
	v_add_co_u32_e32 v30, vcc, s6, v12
	s_nop 1
	v_addc_co_u32_e32 v31, vcc, 0, v13, vcc
	v_add_co_u32_e32 v32, vcc, 0x33000, v12
	s_nop 1
	v_addc_co_u32_e32 v33, vcc, 0, v13, vcc
	v_add_co_u32_e32 v34, vcc, 0x44000, v12
	s_nop 1
	v_addc_co_u32_e32 v35, vcc, 0, v13, vcc
	v_add_co_u32_e32 v36, vcc, 0x55000, v12
	s_nop 1
	v_addc_co_u32_e32 v37, vcc, 0, v13, vcc
	v_add_co_u32_e32 v38, vcc, 0x66000, v12
	s_nop 1
	v_addc_co_u32_e32 v39, vcc, 0, v13, vcc
	v_add_co_u32_e32 v40, vcc, 0x77000, v12
	s_nop 1
	v_addc_co_u32_e32 v41, vcc, 0, v13, vcc
	global_load_dword v57, v[12:13], off
	global_load_dword v56, v[28:29], off offset:32
	global_load_dword v55, v[30:31], off offset:64
	global_load_dword v54, v[32:33], off offset:96
	global_load_dword v52, v[34:35], off offset:128
	global_load_dword v50, v[36:37], off offset:160
	global_load_dword v48, v[38:39], off offset:192
	global_load_dword v46, v[40:41], off offset:224
	v_add_co_u32_e32 v28, vcc, 0x88000, v12
	s_waitcnt vmcnt(7)
	v_cndmask_b32_e64 v57, 0, v57, s[4:5]
	v_addc_co_u32_e32 v29, vcc, 0, v13, vcc
	v_add_co_u32_e32 v30, vcc, 0x99000, v12
	s_nop 1
	v_addc_co_u32_e32 v31, vcc, 0, v13, vcc
	v_add_co_u32_e32 v32, vcc, 0xaa000, v12
	s_nop 1
	v_addc_co_u32_e32 v33, vcc, 0, v13, vcc
	v_add_co_u32_e32 v34, vcc, 0xbb000, v12
	s_nop 1
	v_addc_co_u32_e32 v35, vcc, 0, v13, vcc
	v_add_co_u32_e32 v36, vcc, 0xcc000, v12
	s_nop 1
	v_addc_co_u32_e32 v37, vcc, 0, v13, vcc
	v_add_co_u32_e32 v38, vcc, 0xdd000, v12
	s_nop 1
	v_addc_co_u32_e32 v39, vcc, 0, v13, vcc
	v_add_co_u32_e32 v40, vcc, 0xee000, v12
	s_nop 1
	v_addc_co_u32_e32 v41, vcc, 0, v13, vcc
	v_add_co_u32_e32 v58, vcc, 0xff000, v12
	s_nop 1
	v_addc_co_u32_e32 v59, vcc, 0, v13, vcc
	global_load_dword v53, v[28:29], off offset:256
	global_load_dword v51, v[30:31], off offset:288
	global_load_dword v49, v[32:33], off offset:320
	global_load_dword v47, v[34:35], off offset:352
	global_load_dword v44, v[36:37], off offset:384
	global_load_dword v42, v[38:39], off offset:416
	s_nop 0
	global_load_dword v40, v[40:41], off offset:448
	s_nop 0
	global_load_dword v38, v[58:59], off offset:480
	v_add_co_u32_e32 v28, vcc, 0x110000, v12
	s_nop 1
	v_addc_co_u32_e32 v29, vcc, 0, v13, vcc
	v_add_co_u32_e32 v30, vcc, 0x121000, v12
	s_nop 1
	v_addc_co_u32_e32 v31, vcc, 0, v13, vcc
	v_add_co_u32_e32 v32, vcc, 0x132000, v12
	s_nop 1
	v_addc_co_u32_e32 v33, vcc, 0, v13, vcc
	v_add_co_u32_e32 v34, vcc, 0x143000, v12
	s_nop 1
	v_addc_co_u32_e32 v35, vcc, 0, v13, vcc
	v_add_co_u32_e32 v36, vcc, 0x154000, v12
	s_nop 1
	v_addc_co_u32_e32 v37, vcc, 0, v13, vcc
	v_add_co_u32_e32 v58, vcc, 0x165000, v12
	s_nop 1
	v_addc_co_u32_e32 v59, vcc, 0, v13, vcc
	v_add_co_u32_e32 v60, vcc, 0x176000, v12
	s_nop 1
	v_addc_co_u32_e32 v61, vcc, 0, v13, vcc
	v_add_co_u32_e32 v62, vcc, 0x187000, v12
	s_nop 1
	v_addc_co_u32_e32 v63, vcc, 0, v13, vcc
	global_load_dword v45, v[28:29], off offset:512
	global_load_dword v43, v[30:31], off offset:544
	global_load_dword v41, v[32:33], off offset:576
	global_load_dword v39, v[34:35], off offset:608
	s_nop 0
	global_load_dword v36, v[36:37], off offset:640
	s_nop 0
	global_load_dword v34, v[58:59], off offset:672
	global_load_dword v32, v[60:61], off offset:704
	global_load_dword v30, v[62:63], off offset:736
	v_add_co_u32_e32 v28, vcc, 0x198000, v12
	s_nop 1
	v_addc_co_u32_e32 v29, vcc, 0, v13, vcc
	v_add_co_u32_e32 v58, vcc, 0x1a9000, v12
	s_nop 1
	v_addc_co_u32_e32 v59, vcc, 0, v13, vcc
	v_add_co_u32_e32 v60, vcc, 0x1ba000, v12
	s_nop 1
	v_addc_co_u32_e32 v61, vcc, 0, v13, vcc
	v_add_co_u32_e32 v62, vcc, 0x1cb000, v12
	s_nop 1
	v_addc_co_u32_e32 v63, vcc, 0, v13, vcc
	v_add_co_u32_e32 v64, vcc, 0x1dc000, v12
	s_nop 1
	v_addc_co_u32_e32 v65, vcc, 0, v13, vcc
	v_add_co_u32_e32 v66, vcc, 0x1ed000, v12
	s_nop 1
	v_addc_co_u32_e32 v67, vcc, 0, v13, vcc
	v_add_co_u32_e32 v68, vcc, 0x1fe000, v12
	s_nop 1
	v_addc_co_u32_e32 v69, vcc, 0, v13, vcc
	v_add_co_u32_e32 v12, vcc, 0x20f000, v12
	s_nop 1
	v_addc_co_u32_e32 v13, vcc, 0, v13, vcc
	global_load_dword v37, v[28:29], off offset:768
	global_load_dword v35, v[58:59], off offset:800
	global_load_dword v33, v[60:61], off offset:832
	global_load_dword v31, v[62:63], off offset:864
	s_nop 0
	global_load_dword v29, v[64:65], off offset:896
	global_load_dword v28, v[66:67], off offset:928
	global_load_dword v27, v[68:69], off offset:960
	global_load_dword v0, v[12:13], off offset:992
	v_cndmask_b32_e64 v58, 0, 1, s[12:13]
	v_lshl_add_u64 v[12:13], s[14:15], 2, v[8:9]
	v_cmp_ne_u32_e64 s[6:7], 1, v58
	s_andn2_b64 vcc, exec, s[12:13]
	s_cbranch_vccnz .LBB0_50
	global_load_dword v142, v[12:13], off
	global_load_dword v143, v[12:13], off offset:8
	global_load_dword v144, v[12:13], off offset:16
	global_load_dword v145, v[12:13], off offset:24
	global_load_dword v146, v[12:13], off offset:32
	global_load_dword v147, v[12:13], off offset:40
	global_load_dword v148, v[12:13], off offset:48
	global_load_dword v149, v[12:13], off offset:56
	global_load_dword v150, v[12:13], off offset:64
	global_load_dword v151, v[12:13], off offset:72
	global_load_dword v152, v[12:13], off offset:80
	global_load_dword v153, v[12:13], off offset:88
	global_load_dword v154, v[12:13], off offset:96
	global_load_dword v155, v[12:13], off offset:104
	global_load_dword v156, v[12:13], off offset:112
	global_load_dword v157, v[12:13], off offset:120
	global_load_dword v158, v[12:13], off offset:128
	global_load_dword v159, v[12:13], off offset:136
	global_load_dword v168, v[12:13], off offset:144
	global_load_dword v169, v[12:13], off offset:152
	global_load_dword v170, v[12:13], off offset:160
	global_load_dword v171, v[12:13], off offset:168
	global_load_dword v172, v[12:13], off offset:176
	global_load_dword v173, v[12:13], off offset:184
	global_load_dword v174, v[12:13], off offset:192
	global_load_dword v175, v[12:13], off offset:200
	global_load_dword v176, v[12:13], off offset:208
	global_load_dword v177, v[12:13], off offset:216
	global_load_dword v178, v[12:13], off offset:224
	global_load_dword v179, v[12:13], off offset:232
	global_load_dword v180, v[12:13], off offset:240
	global_load_dword v181, v[12:13], off offset:248
	s_waitcnt vmcnt(0)
	v_mul_f32_e32 v57, v57, v142
.LBB0_50:
	s_and_b64 vcc, exec, s[6:7]
	s_waitcnt vmcnt(30)
	v_cndmask_b32_e64 v56, 0, v56, s[4:5]
	ds_write_b32 v14, v57
	s_cbranch_vccnz .LBB0_52
	v_mul_f32_e32 v56, v56, v143
.LBB0_52:
	s_and_b64 vcc, exec, s[6:7]
	s_waitcnt vmcnt(29)
	v_cndmask_b32_e64 v55, 0, v55, s[4:5]
	ds_write_b32 v14, v56 offset:264
	s_cbranch_vccnz .LBB0_54
	v_mul_f32_e32 v55, v55, v144
.LBB0_54:
	s_and_b64 vcc, exec, s[6:7]
	s_waitcnt vmcnt(28)
	v_cndmask_b32_e64 v54, 0, v54, s[4:5]
	ds_write_b32 v14, v55 offset:528
	s_cbranch_vccnz .LBB0_56
	v_mul_f32_e32 v54, v54, v145
.LBB0_56:
	s_and_b64 vcc, exec, s[6:7]
	s_waitcnt vmcnt(27)
	v_cndmask_b32_e64 v52, 0, v52, s[4:5]
	ds_write_b32 v14, v54 offset:792
	s_cbranch_vccnz .LBB0_58
	v_mul_f32_e32 v52, v52, v146
.LBB0_58:
	s_and_b64 vcc, exec, s[6:7]
	s_waitcnt vmcnt(26)
	v_cndmask_b32_e64 v50, 0, v50, s[4:5]
	ds_write_b32 v14, v52 offset:1056
	s_cbranch_vccnz .LBB0_60
	v_mul_f32_e32 v50, v50, v147
.LBB0_60:
	s_and_b64 vcc, exec, s[6:7]
	s_waitcnt vmcnt(25)
	v_cndmask_b32_e64 v48, 0, v48, s[4:5]
	ds_write_b32 v14, v50 offset:1320
	s_cbranch_vccnz .LBB0_62
	v_mul_f32_e32 v48, v48, v148
.LBB0_62:
	s_and_b64 vcc, exec, s[6:7]
	s_waitcnt vmcnt(24)
	v_cndmask_b32_e64 v46, 0, v46, s[4:5]
	ds_write_b32 v14, v48 offset:1584
	s_cbranch_vccnz .LBB0_64
	v_mul_f32_e32 v46, v46, v149
.LBB0_64:
	ds_write_b32 v14, v46 offset:1848
	s_and_b64 vcc, exec, s[6:7]
	s_waitcnt vmcnt(23)
	v_cndmask_b32_e64 v46, 0, v53, s[4:5]
	s_cbranch_vccnz .LBB0_66
	v_mul_f32_e32 v46, v46, v150
.LBB0_66:
	ds_write_b32 v14, v46 offset:2112
	s_and_b64 vcc, exec, s[6:7]
	s_waitcnt vmcnt(22)
	v_cndmask_b32_e64 v46, 0, v51, s[4:5]
	s_cbranch_vccnz .LBB0_68
	v_mul_f32_e32 v46, v46, v151
.LBB0_68:
	ds_write_b32 v14, v46 offset:2376
	s_and_b64 vcc, exec, s[6:7]
	s_waitcnt vmcnt(21)
	v_cndmask_b32_e64 v46, 0, v49, s[4:5]
	s_cbranch_vccnz .LBB0_70
	v_mul_f32_e32 v46, v46, v152
.LBB0_70:
	ds_write_b32 v14, v46 offset:2640
	s_and_b64 vcc, exec, s[6:7]
	s_waitcnt vmcnt(20)
	v_cndmask_b32_e64 v46, 0, v47, s[4:5]
	s_cbranch_vccnz .LBB0_72
	v_mul_f32_e32 v46, v46, v153
.LBB0_72:
	s_and_b64 vcc, exec, s[6:7]
	s_waitcnt vmcnt(19)
	v_cndmask_b32_e64 v44, 0, v44, s[4:5]
	ds_write_b32 v14, v46 offset:2904
	s_cbranch_vccnz .LBB0_74
	v_mul_f32_e32 v44, v44, v154
.LBB0_74:
	s_and_b64 vcc, exec, s[6:7]
	s_waitcnt vmcnt(18)
	v_cndmask_b32_e64 v42, 0, v42, s[4:5]
	ds_write_b32 v14, v44 offset:3168
	s_cbranch_vccnz .LBB0_76
	v_mul_f32_e32 v42, v42, v155
.LBB0_76:
	s_and_b64 vcc, exec, s[6:7]
	s_waitcnt vmcnt(17)
	v_cndmask_b32_e64 v40, 0, v40, s[4:5]
	ds_write_b32 v14, v42 offset:3432
	s_cbranch_vccnz .LBB0_78
	v_mul_f32_e32 v40, v40, v156
.LBB0_78:
	s_and_b64 vcc, exec, s[6:7]
	s_waitcnt vmcnt(16)
	v_cndmask_b32_e64 v38, 0, v38, s[4:5]
	ds_write_b32 v14, v40 offset:3696
	s_cbranch_vccnz .LBB0_80
	v_mul_f32_e32 v38, v38, v157
.LBB0_80:
	ds_write_b32 v14, v38 offset:3960
	s_and_b64 vcc, exec, s[6:7]
	s_waitcnt vmcnt(15)
	v_cndmask_b32_e64 v38, 0, v45, s[4:5]
	s_cbranch_vccnz .LBB0_82
	v_mul_f32_e32 v38, v38, v158
.LBB0_82:
	ds_write_b32 v14, v38 offset:4224
	s_and_b64 vcc, exec, s[6:7]
	s_waitcnt vmcnt(14)
	v_cndmask_b32_e64 v38, 0, v43, s[4:5]
	s_cbranch_vccnz .LBB0_84
	v_mul_f32_e32 v38, v38, v159
.LBB0_84:
	ds_write_b32 v14, v38 offset:4488
	s_and_b64 vcc, exec, s[6:7]
	s_waitcnt vmcnt(13)
	v_cndmask_b32_e64 v38, 0, v41, s[4:5]
	s_cbranch_vccnz .LBB0_86
	v_mul_f32_e32 v38, v38, v168
.LBB0_86:
	ds_write_b32 v14, v38 offset:4752
	s_and_b64 vcc, exec, s[6:7]
	s_waitcnt vmcnt(12)
	v_cndmask_b32_e64 v38, 0, v39, s[4:5]
	s_cbranch_vccnz .LBB0_88
	v_mul_f32_e32 v38, v38, v169
.LBB0_88:
	s_and_b64 vcc, exec, s[6:7]
	s_waitcnt vmcnt(11)
	v_cndmask_b32_e64 v36, 0, v36, s[4:5]
	ds_write_b32 v14, v38 offset:5016
	s_cbranch_vccnz .LBB0_90
	v_mul_f32_e32 v36, v36, v170
.LBB0_90:
	s_and_b64 vcc, exec, s[6:7]
	s_waitcnt vmcnt(10)
	v_cndmask_b32_e64 v34, 0, v34, s[4:5]
	ds_write_b32 v14, v36 offset:5280
	s_cbranch_vccnz .LBB0_92
	v_mul_f32_e32 v34, v34, v171
.LBB0_92:
	s_and_b64 vcc, exec, s[6:7]
	s_waitcnt vmcnt(9)
	v_cndmask_b32_e64 v32, 0, v32, s[4:5]
	ds_write_b32 v14, v34 offset:5544
	s_cbranch_vccnz .LBB0_94
	v_mul_f32_e32 v32, v32, v172
.LBB0_94:
	s_and_b64 vcc, exec, s[6:7]
	s_waitcnt vmcnt(8)
	v_cndmask_b32_e64 v30, 0, v30, s[4:5]
	ds_write_b32 v14, v32 offset:5808
	s_cbranch_vccnz .LBB0_96
	v_mul_f32_e32 v30, v30, v173
.LBB0_96:
	ds_write_b32 v14, v30 offset:6072
	s_and_b64 vcc, exec, s[6:7]
	s_waitcnt vmcnt(7)
	v_cndmask_b32_e64 v30, 0, v37, s[4:5]
	s_cbranch_vccnz .LBB0_98
	v_mul_f32_e32 v30, v30, v174
.LBB0_98:
	ds_write_b32 v14, v30 offset:6336
	s_and_b64 vcc, exec, s[6:7]
	s_waitcnt vmcnt(6)
	v_cndmask_b32_e64 v30, 0, v35, s[4:5]
	s_cbranch_vccnz .LBB0_100
	v_mul_f32_e32 v30, v30, v175
.LBB0_100:
	ds_write_b32 v14, v30 offset:6600
	s_and_b64 vcc, exec, s[6:7]
	s_waitcnt vmcnt(5)
	v_cndmask_b32_e64 v30, 0, v33, s[4:5]
	s_cbranch_vccnz .LBB0_102
	v_mul_f32_e32 v30, v30, v176
.LBB0_102:
	ds_write_b32 v14, v30 offset:6864
	s_and_b64 vcc, exec, s[6:7]
	s_waitcnt vmcnt(4)
	v_cndmask_b32_e64 v30, 0, v31, s[4:5]
	s_cbranch_vccnz .LBB0_104
	v_mul_f32_e32 v30, v30, v177
.LBB0_104:
	s_and_b64 vcc, exec, s[6:7]
	s_waitcnt vmcnt(3)
	v_cndmask_b32_e64 v29, 0, v29, s[4:5]
	ds_write_b32 v14, v30 offset:7128
	s_cbranch_vccnz .LBB0_106
	v_mul_f32_e32 v29, v29, v178
.LBB0_106:
	s_and_b64 vcc, exec, s[6:7]
	s_waitcnt vmcnt(2)
	v_cndmask_b32_e64 v28, 0, v28, s[4:5]
	ds_write_b32 v14, v29 offset:7392
	s_cbranch_vccnz .LBB0_108
	v_mul_f32_e32 v28, v28, v179
.LBB0_108:
	s_and_b64 vcc, exec, s[6:7]
	s_waitcnt vmcnt(1)
	v_cndmask_b32_e64 v27, 0, v27, s[4:5]
	ds_write_b32 v14, v28 offset:7656
	s_cbranch_vccnz .LBB0_110
	v_mul_f32_e32 v27, v27, v180
.LBB0_110:
	s_and_b64 vcc, exec, s[6:7]
	s_waitcnt vmcnt(0)
	v_cndmask_b32_e64 v0, 0, v0, s[4:5]
	ds_write_b32 v14, v27 offset:7920
	s_cbranch_vccnz .LBB0_30
	v_mul_f32_e32 v0, v0, v181
	s_branch .LBB0_30

.LBB0_711:
	s_andn2_b64 vcc, exec, s[4:5]
	s_cbranch_vccnz .LBB0_708
	s_ashr_i32 s4, s3, 31
	s_lshr_b32 s4, s4, 25
	s_add_i32 s4, s3, s4
	s_ashr_i32 s5, s4, 7
	s_and_b32 s4, s4, 0xffffff80
	s_lshl_b32 s24, s5, 12
	s_sub_i32 s4, s3, s4
	s_lshl_b32 s14, s5, 6
	s_sub_i32 s5, s16, s24
	s_cmp_gt_i32 s4, -1
	v_or_b32_e32 v8, s14, v11
	v_add_u32_e32 v0, s5, v10
	s_cselect_b64 s[4:5], -1, 0
	v_ashrrev_i32_e32 v9, 31, v8
	v_lshlrev_b64 v[8:9], 14, v[8:9]
	v_cndmask_b32_e64 v20, 0, v0, s[4:5]
	v_lshl_add_u64 v[8:9], s[0:1], 0, v[8:9]
	v_ashrrev_i32_e32 v21, 31, v20
	v_lshl_add_u64 v[8:9], v[20:21], 2, v[8:9]
	s_mov_b32 s6, 0x8000
	v_add_co_u32_e32 v20, vcc, s6, v8
	s_mov_b32 s6, 0x10000
	s_nop 0
	v_addc_co_u32_e32 v21, vcc, 0, v9, vcc
	global_load_dword v29, v[8:9], off
	global_load_dword v49, v[20:21], off
	v_add_co_u32_e32 v20, vcc, s6, v8
	s_mov_b32 s6, 0x18000
	s_nop 0
	v_addc_co_u32_e32 v21, vcc, 0, v9, vcc
	global_load_dword v48, v[20:21], off
	v_add_co_u32_e32 v20, vcc, s6, v8
	s_mov_b32 s6, 0x20000
	s_nop 0
	v_addc_co_u32_e32 v21, vcc, 0, v9, vcc
	global_load_dword v46, v[20:21], off
	v_add_co_u32_e32 v20, vcc, s6, v8
	s_mov_b32 s6, 0x28000
	s_nop 0
	v_addc_co_u32_e32 v21, vcc, 0, v9, vcc
	global_load_dword v45, v[20:21], off
	v_add_co_u32_e32 v20, vcc, s6, v8
	s_mov_b32 s6, 0x30000
	s_nop 0
	v_addc_co_u32_e32 v21, vcc, 0, v9, vcc
	global_load_dword v43, v[20:21], off
	v_add_co_u32_e32 v20, vcc, s6, v8
	s_mov_b32 s6, 0x38000
	s_nop 0
	v_addc_co_u32_e32 v21, vcc, 0, v9, vcc
	global_load_dword v41, v[20:21], off
	v_add_co_u32_e32 v20, vcc, s6, v8
	s_mov_b32 s6, 0x40000
	s_nop 0
	v_addc_co_u32_e32 v21, vcc, 0, v9, vcc
	global_load_dword v47, v[20:21], off
	v_add_co_u32_e32 v20, vcc, s6, v8
	s_mov_b32 s6, 0x48000
	s_nop 0
	v_addc_co_u32_e32 v21, vcc, 0, v9, vcc
	global_load_dword v44, v[20:21], off
	v_add_co_u32_e32 v20, vcc, s6, v8
	s_mov_b32 s6, 0x50000
	s_nop 0
	v_addc_co_u32_e32 v21, vcc, 0, v9, vcc
	global_load_dword v42, v[20:21], off
	v_add_co_u32_e32 v20, vcc, s6, v8
	s_mov_b32 s6, 0x58000
	s_nop 0
	v_addc_co_u32_e32 v21, vcc, 0, v9, vcc
	global_load_dword v40, v[20:21], off
	v_add_co_u32_e32 v20, vcc, s6, v8
	s_mov_b32 s6, 0x60000
	s_nop 0
	v_addc_co_u32_e32 v21, vcc, 0, v9, vcc
	global_load_dword v38, v[20:21], off
	v_add_co_u32_e32 v20, vcc, s6, v8
	s_mov_b32 s6, 0x68000
	s_nop 0
	v_addc_co_u32_e32 v21, vcc, 0, v9, vcc
	global_load_dword v37, v[20:21], off
	v_add_co_u32_e32 v20, vcc, s6, v8
	s_mov_b32 s6, 0x70000
	s_nop 0
	v_addc_co_u32_e32 v21, vcc, 0, v9, vcc
	global_load_dword v35, v[20:21], off
	v_add_co_u32_e32 v20, vcc, s6, v8
	s_mov_b32 s6, 0x78000
	s_nop 0
	v_addc_co_u32_e32 v21, vcc, 0, v9, vcc
	global_load_dword v33, v[20:21], off
	v_add_co_u32_e32 v20, vcc, s6, v8
	s_mov_b32 s6, 0x80000
	s_nop 0
	v_addc_co_u32_e32 v21, vcc, 0, v9, vcc
	global_load_dword v39, v[20:21], off
	v_add_co_u32_e32 v20, vcc, s6, v8
	s_mov_b32 s6, 0x88000
	s_nop 0
	v_addc_co_u32_e32 v21, vcc, 0, v9, vcc
	global_load_dword v36, v[20:21], off
	v_add_co_u32_e32 v20, vcc, s6, v8
	s_mov_b32 s6, 0x90000
	s_nop 0
	v_addc_co_u32_e32 v21, vcc, 0, v9, vcc
	global_load_dword v34, v[20:21], off
	v_add_co_u32_e32 v20, vcc, s6, v8
	s_mov_b32 s6, 0x98000
	s_nop 0
	v_addc_co_u32_e32 v21, vcc, 0, v9, vcc
	global_load_dword v32, v[20:21], off
	v_add_co_u32_e32 v20, vcc, s6, v8
	s_mov_b32 s6, 0xa0000
	s_nop 0
	v_addc_co_u32_e32 v21, vcc, 0, v9, vcc
	global_load_dword v30, v[20:21], off
	v_add_co_u32_e32 v20, vcc, s6, v8
	s_mov_b32 s6, 0xa8000
	s_nop 0
	v_addc_co_u32_e32 v21, vcc, 0, v9, vcc
	global_load_dword v28, v[20:21], off
	v_add_co_u32_e32 v20, vcc, s6, v8
	s_mov_b32 s6, 0xb0000
	s_nop 0
	v_addc_co_u32_e32 v21, vcc, 0, v9, vcc
	global_load_dword v26, v[20:21], off
	v_add_co_u32_e32 v20, vcc, s6, v8
	s_mov_b32 s6, 0xb8000
	s_nop 0
	v_addc_co_u32_e32 v21, vcc, 0, v9, vcc
	global_load_dword v23, v[20:21], off
	v_add_co_u32_e32 v20, vcc, s6, v8
	s_mov_b32 s6, 0xc0000
	s_nop 0
	v_addc_co_u32_e32 v21, vcc, 0, v9, vcc
	global_load_dword v31, v[20:21], off
	v_add_co_u32_e32 v20, vcc, s6, v8
	s_mov_b32 s6, 0xc8000
	s_nop 0
	v_addc_co_u32_e32 v21, vcc, 0, v9, vcc
	global_load_dword v27, v[20:21], off
	v_add_co_u32_e32 v20, vcc, s6, v8
	s_mov_b32 s6, 0xd0000
	s_nop 0
	v_addc_co_u32_e32 v21, vcc, 0, v9, vcc
	global_load_dword v24, v[20:21], off
	v_add_co_u32_e32 v20, vcc, s6, v8
	s_mov_b32 s6, 0xd8000
	s_nop 0
	v_addc_co_u32_e32 v21, vcc, 0, v9, vcc
	global_load_dword v22, v[20:21], off
	v_add_co_u32_e32 v20, vcc, s6, v8
	s_mov_b32 s6, 0xe0000
	s_nop 0
	v_addc_co_u32_e32 v21, vcc, 0, v9, vcc
	v_add_co_u32_e32 v50, vcc, s6, v8
	s_mov_b32 s6, 0xe8000
	s_nop 0
	v_addc_co_u32_e32 v51, vcc, 0, v9, vcc
	global_load_dword v21, v[20:21], off
	s_ashr_i32 s15, s14, 31
	global_load_dword v20, v[50:51], off
	v_add_co_u32_e32 v50, vcc, s6, v8
	s_nop 1
	v_addc_co_u32_e32 v51, vcc, 0, v9, vcc
	global_load_dword v19, v[50:51], off
	v_add_co_u32_e32 v50, vcc, 0xf0000, v8
	s_nop 1
	v_addc_co_u32_e32 v51, vcc, 0, v9, vcc
	v_add_co_u32_e32 v8, vcc, 0xf8000, v8
	global_load_dword v0, v[50:51], off
	s_nop 0
	v_addc_co_u32_e32 v9, vcc, 0, v9, vcc
	global_load_dword v25, v[8:9], off
	v_cndmask_b32_e64 v50, 0, 1, s[12:13]
	v_lshl_add_u64 v[8:9], s[14:15], 2, v[4:5]
	v_cmp_ne_u32_e64 s[6:7], 1, v50
	s_andn2_b64 vcc, exec, s[12:13]
	s_waitcnt vmcnt(31)
	v_cndmask_b32_e64 v50, 0, v29, s[4:5]
	s_cbranch_vccnz .LBB0_714
	global_load_dword v142, v[8:9], off
	global_load_dword v143, v[8:9], off offset:8
	global_load_dword v144, v[8:9], off offset:16
	global_load_dword v145, v[8:9], off offset:24
	global_load_dword v146, v[8:9], off offset:32
	global_load_dword v147, v[8:9], off offset:40
	global_load_dword v148, v[8:9], off offset:48
	global_load_dword v149, v[8:9], off offset:56
	global_load_dword v150, v[8:9], off offset:64
	global_load_dword v151, v[8:9], off offset:72
	global_load_dword v152, v[8:9], off offset:80
	global_load_dword v153, v[8:9], off offset:88
	global_load_dword v154, v[8:9], off offset:96
	global_load_dword v155, v[8:9], off offset:104
	global_load_dword v156, v[8:9], off offset:112
	global_load_dword v157, v[8:9], off offset:120
	global_load_dword v158, v[8:9], off offset:128
	global_load_dword v159, v[8:9], off offset:136
	global_load_dword v168, v[8:9], off offset:144
	global_load_dword v169, v[8:9], off offset:152
	global_load_dword v170, v[8:9], off offset:160
	global_load_dword v171, v[8:9], off offset:168
	global_load_dword v172, v[8:9], off offset:176
	global_load_dword v173, v[8:9], off offset:184
	global_load_dword v174, v[8:9], off offset:192
	global_load_dword v175, v[8:9], off offset:200
	global_load_dword v176, v[8:9], off offset:208
	global_load_dword v177, v[8:9], off offset:216
	global_load_dword v178, v[8:9], off offset:224
	global_load_dword v179, v[8:9], off offset:232
	global_load_dword v180, v[8:9], off offset:240
	global_load_dword v181, v[8:9], off offset:248
	s_waitcnt vmcnt(0)
	v_mul_f32_e32 v50, v50, v142
.LBB0_714:
	v_add_u32_e32 v29, v12, v13
	s_and_b64 vcc, exec, s[6:7]
	s_waitcnt vmcnt(30)
	v_cndmask_b32_e64 v49, 0, v49, s[4:5]
	ds_write_b32 v29, v50
	s_cbranch_vccnz .LBB0_716
	v_mul_f32_e32 v49, v49, v143
.LBB0_716:
	s_and_b64 vcc, exec, s[6:7]
	s_waitcnt vmcnt(29)
	v_cndmask_b32_e64 v48, 0, v48, s[4:5]
	ds_write_b32 v29, v49 offset:264
	s_cbranch_vccnz .LBB0_718
	v_mul_f32_e32 v48, v48, v144
.LBB0_718:
	s_and_b64 vcc, exec, s[6:7]
	s_waitcnt vmcnt(28)
	v_cndmask_b32_e64 v46, 0, v46, s[4:5]
	ds_write_b32 v29, v48 offset:528
	s_cbranch_vccnz .LBB0_720
	v_mul_f32_e32 v46, v46, v145
.LBB0_720:
	s_and_b64 vcc, exec, s[6:7]
	s_waitcnt vmcnt(27)
	v_cndmask_b32_e64 v45, 0, v45, s[4:5]
	ds_write_b32 v29, v46 offset:792
	s_cbranch_vccnz .LBB0_722
	v_mul_f32_e32 v45, v45, v146
.LBB0_722:
	s_and_b64 vcc, exec, s[6:7]
	s_waitcnt vmcnt(26)
	v_cndmask_b32_e64 v43, 0, v43, s[4:5]
	ds_write_b32 v29, v45 offset:1056
	s_cbranch_vccnz .LBB0_724
	v_mul_f32_e32 v43, v43, v147
.LBB0_724:
	s_and_b64 vcc, exec, s[6:7]
	s_waitcnt vmcnt(25)
	v_cndmask_b32_e64 v41, 0, v41, s[4:5]
	ds_write_b32 v29, v43 offset:1320
	s_cbranch_vccnz .LBB0_726
	v_mul_f32_e32 v41, v41, v148
.LBB0_726:
	ds_write_b32 v29, v41 offset:1584
	s_and_b64 vcc, exec, s[6:7]
	s_waitcnt vmcnt(24)
	v_cndmask_b32_e64 v41, 0, v47, s[4:5]
	s_cbranch_vccnz .LBB0_728
	v_mul_f32_e32 v41, v41, v149
.LBB0_728:
	ds_write_b32 v29, v41 offset:1848
	s_and_b64 vcc, exec, s[6:7]
	s_waitcnt vmcnt(23)
	v_cndmask_b32_e64 v41, 0, v44, s[4:5]
	s_cbranch_vccnz .LBB0_730
	v_mul_f32_e32 v41, v41, v150
.LBB0_730:
	ds_write_b32 v29, v41 offset:2112
	s_and_b64 vcc, exec, s[6:7]
	s_waitcnt vmcnt(22)
	v_cndmask_b32_e64 v41, 0, v42, s[4:5]
	s_cbranch_vccnz .LBB0_732
	v_mul_f32_e32 v41, v41, v151
.LBB0_732:
	s_and_b64 vcc, exec, s[6:7]
	s_waitcnt vmcnt(21)
	v_cndmask_b32_e64 v40, 0, v40, s[4:5]
	ds_write_b32 v29, v41 offset:2376
	s_cbranch_vccnz .LBB0_734
	v_mul_f32_e32 v40, v40, v152
.LBB0_734:
	s_and_b64 vcc, exec, s[6:7]
	s_waitcnt vmcnt(20)
	v_cndmask_b32_e64 v38, 0, v38, s[4:5]
	ds_write_b32 v29, v40 offset:2640
	s_cbranch_vccnz .LBB0_736
	v_mul_f32_e32 v38, v38, v153
.LBB0_736:
	s_and_b64 vcc, exec, s[6:7]
	s_waitcnt vmcnt(19)
	v_cndmask_b32_e64 v37, 0, v37, s[4:5]
	ds_write_b32 v29, v38 offset:2904
	s_cbranch_vccnz .LBB0_738
	v_mul_f32_e32 v37, v37, v154
.LBB0_738:
	s_and_b64 vcc, exec, s[6:7]
	s_waitcnt vmcnt(18)
	v_cndmask_b32_e64 v35, 0, v35, s[4:5]
	ds_write_b32 v29, v37 offset:3168
	s_cbranch_vccnz .LBB0_740
	v_mul_f32_e32 v35, v35, v155
.LBB0_740:
	s_and_b64 vcc, exec, s[6:7]
	s_waitcnt vmcnt(17)
	v_cndmask_b32_e64 v33, 0, v33, s[4:5]
	ds_write_b32 v29, v35 offset:3432
	s_cbranch_vccnz .LBB0_742
	v_mul_f32_e32 v33, v33, v156
.LBB0_742:
	ds_write_b32 v29, v33 offset:3696
	s_and_b64 vcc, exec, s[6:7]
	s_waitcnt vmcnt(16)
	v_cndmask_b32_e64 v33, 0, v39, s[4:5]
	s_cbranch_vccnz .LBB0_744
	v_mul_f32_e32 v33, v33, v157
.LBB0_744:
	ds_write_b32 v29, v33 offset:3960
	s_and_b64 vcc, exec, s[6:7]
	s_waitcnt vmcnt(15)
	v_cndmask_b32_e64 v33, 0, v36, s[4:5]
	s_cbranch_vccnz .LBB0_746
	v_mul_f32_e32 v33, v33, v158
.LBB0_746:
	ds_write_b32 v29, v33 offset:4224
	s_and_b64 vcc, exec, s[6:7]
	s_waitcnt vmcnt(14)
	v_cndmask_b32_e64 v33, 0, v34, s[4:5]
	s_cbranch_vccnz .LBB0_748
	v_mul_f32_e32 v33, v33, v159
.LBB0_748:
	s_and_b64 vcc, exec, s[6:7]
	s_waitcnt vmcnt(13)
	v_cndmask_b32_e64 v32, 0, v32, s[4:5]
	ds_write_b32 v29, v33 offset:4488
	s_cbranch_vccnz .LBB0_750
	v_mul_f32_e32 v32, v32, v168
.LBB0_750:
	s_and_b64 vcc, exec, s[6:7]
	s_waitcnt vmcnt(12)
	v_cndmask_b32_e64 v30, 0, v30, s[4:5]
	ds_write_b32 v29, v32 offset:4752
	s_cbranch_vccnz .LBB0_752
	v_mul_f32_e32 v30, v30, v169
.LBB0_752:
	s_and_b64 vcc, exec, s[6:7]
	s_waitcnt vmcnt(11)
	v_cndmask_b32_e64 v28, 0, v28, s[4:5]
	ds_write_b32 v29, v30 offset:5016
	s_cbranch_vccnz .LBB0_754
	v_mul_f32_e32 v28, v28, v170
.LBB0_754:
	s_and_b64 vcc, exec, s[6:7]
	s_waitcnt vmcnt(10)
	v_cndmask_b32_e64 v26, 0, v26, s[4:5]
	ds_write_b32 v29, v28 offset:5280
	s_cbranch_vccnz .LBB0_756
	v_mul_f32_e32 v26, v26, v171
.LBB0_756:
	s_and_b64 vcc, exec, s[6:7]
	s_waitcnt vmcnt(9)
	v_cndmask_b32_e64 v23, 0, v23, s[4:5]
	ds_write_b32 v29, v26 offset:5544
	s_cbranch_vccnz .LBB0_758
	v_mul_f32_e32 v23, v23, v172
.LBB0_758:
	ds_write_b32 v29, v23 offset:5808
	s_and_b64 vcc, exec, s[6:7]
	s_waitcnt vmcnt(8)
	v_cndmask_b32_e64 v23, 0, v31, s[4:5]
	s_cbranch_vccnz .LBB0_760
	v_mul_f32_e32 v23, v23, v173
.LBB0_760:
	ds_write_b32 v29, v23 offset:6072
	s_and_b64 vcc, exec, s[6:7]
	s_waitcnt vmcnt(7)
	v_cndmask_b32_e64 v23, 0, v27, s[4:5]
	s_cbranch_vccnz .LBB0_762
	v_mul_f32_e32 v23, v23, v174
.LBB0_762:
	ds_write_b32 v29, v23 offset:6336
	s_and_b64 vcc, exec, s[6:7]
	s_waitcnt vmcnt(6)
	v_cndmask_b32_e64 v23, 0, v24, s[4:5]
	s_cbranch_vccnz .LBB0_764
	v_mul_f32_e32 v23, v23, v175
.LBB0_764:
	s_and_b64 vcc, exec, s[6:7]
	s_waitcnt vmcnt(5)
	v_cndmask_b32_e64 v22, 0, v22, s[4:5]
	ds_write_b32 v29, v23 offset:6600
	s_cbranch_vccnz .LBB0_766
	v_mul_f32_e32 v22, v22, v176
.LBB0_766:
	s_and_b64 vcc, exec, s[6:7]
	s_waitcnt vmcnt(4)
	v_cndmask_b32_e64 v21, 0, v21, s[4:5]
	ds_write_b32 v29, v22 offset:6864
	s_cbranch_vccnz .LBB0_768
	v_mul_f32_e32 v21, v21, v177
.LBB0_768:
	s_and_b64 vcc, exec, s[6:7]
	s_waitcnt vmcnt(3)
	v_cndmask_b32_e64 v20, 0, v20, s[4:5]
	ds_write_b32 v29, v21 offset:7128
	s_cbranch_vccnz .LBB0_770
	v_mul_f32_e32 v20, v20, v178
.LBB0_770:
	s_and_b64 vcc, exec, s[6:7]
	s_waitcnt vmcnt(2)
	v_cndmask_b32_e64 v19, 0, v19, s[4:5]
	ds_write_b32 v29, v20 offset:7392
	s_cbranch_vccnz .LBB0_772
	v_mul_f32_e32 v19, v19, v179
.LBB0_772:
	s_and_b64 vcc, exec, s[6:7]
	s_waitcnt vmcnt(1)
	v_cndmask_b32_e64 v0, 0, v0, s[4:5]
	ds_write_b32 v29, v19 offset:7656
	s_cbranch_vccnz .LBB0_774
	v_mul_f32_e32 v0, v0, v180
.LBB0_774:
	ds_write_b32 v29, v0 offset:7920
	s_and_b64 vcc, exec, s[6:7]
	s_waitcnt vmcnt(0)
	v_cndmask_b32_e64 v0, 0, v25, s[4:5]
	s_cbranch_vccnz .LBB0_707
	v_mul_f32_e32 v0, v0, v181
	s_branch .LBB0_707
